# P1: workgroups 232-247 prefetch the memory K/V projection's first K-tiles with their last w_in tile's trailing stage loads; that GEMM's prologue loads dropped
# baseline (speedup 1.0000x reference)
.LBB0_220:
	v_cndmask_b32_e64 v0, 0, 1, s[0:1]
	v_cmp_ne_u32_e64 s[10:11], 1, v0
	s_andn2_b64 vcc, exec, s[0:1]
	s_mov_b64 s[68:69], s[6:7]
	s_sub_i32 s101, s2, 0xe8
	s_cmp_lt_u32 s101, 16
	s_cbranch_scc0 .Lmk_noA
	s_and_b32 s100, s101, 7
	s_lshl_b32 s100, s100, 1
	s_lshr_b32 s101, s101, 3
	s_add_i32 s100, s100, s101
	s_and_b32 s101, s100, 7
	s_lshl_b32 s101, s101, 19
	s_add_u32 s68, s36, s101
	s_addc_u32 s69, s37, 0
	s_add_u32 s68, s68, 0x2400000
	s_addc_u32 s69, s69, 0
	s_mov_b32 s100, 0
.Lmk_noA:
	s_cbranch_vccnz .LBB0_222
	s_ashr_i32 s0, s73, 31
	s_mul_hi_u32 s1, s12, s73
	s_mul_i32 s0, s12, s0
	s_add_i32 s0, s1, s0
	s_mul_i32 s1, s13, s73
	s_add_i32 s0, s0, s1
	s_mul_i32 s1, s12, s73
	s_add_u32 s68, s36, s1
	s_addc_u32 s69, s37, s0
.LBB0_222:
	s_and_b64 vcc, exec, s[10:11]
	s_mov_b64 s[86:87], s[4:5]
	s_sub_i32 s101, s2, 0xe8
	s_cmp_lt_u32 s101, 16
	s_cbranch_scc0 .Lmk_noB
	s_and_b32 s100, s101, 7
	s_lshl_b32 s100, s100, 1
	s_lshr_b32 s101, s101, 3
	s_add_i32 s100, s100, s101
	s_lshr_b32 s101, s100, 3
	s_lshl_b32 s101, s101, 19
	s_add_u32 s86, s59, s101
	s_addc_u32 s87, s62, 0
	s_add_u32 s86, s86, 0x1380000
	s_addc_u32 s87, s87, 0
	s_mov_b32 s100, 0
.Lmk_noB:
	s_cbranch_vccnz .LBB0_224
	s_ashr_i32 s0, s72, 31
	s_mul_hi_u32 s1, s12, s72
	s_mul_i32 s0, s12, s0
	s_add_i32 s0, s1, s0
	s_mul_i32 s1, s13, s72
	s_add_i32 s0, s0, s1
	s_mul_i32 s1, s12, s72
	s_add_u32 s86, s59, s1
	s_addc_u32 s87, s62, s0

.LBB0_335:
	v_bfe_i32 v2, v18, 27, 1
	v_lshlrev_b32_e32 v0, 4, v18
	v_lshrrev_b32_e32 v2, 22, v2
	v_add_u32_e32 v2, v0, v2
	v_and_b32_e32 v2, 0xfffffc00, v2
	v_sub_u32_e32 v2, v0, v2
	v_ashrrev_i32_e32 v1, 31, v18
	v_lshrrev_b32_e32 v3, 4, v2
	v_lshrrev_b32_e32 v1, 26, v1
	v_bitop3_b32 v2, v3, v2, 32 bitop3:0x6c
	v_add_u32_e32 v1, v18, v1
	v_ashrrev_i32_e32 v4, 31, v2
	s_mul_i32 s4, s92, 0x2500000
	v_ashrrev_i32_e32 v1, 6, v1
	v_lshrrev_b32_e32 v4, 26, v4
	s_mul_hi_u32 s1, s92, 0x2500000
	s_add_u32 s4, s63, s4
	v_lshlrev_b32_e32 v3, 3, v1
	v_add_u32_e32 v4, v2, v4
	s_addc_u32 s1, s65, s1
	v_and_b32_e32 v3, -16, v3
	v_ashrrev_i32_e32 v5, 6, v4
	v_lshlrev_b32_e32 v1, 5, v1
	s_add_u32 s20, s4, 0x1380000
	v_add_u32_e32 v3, v5, v3
	v_and_b32_e32 v12, 32, v1
	v_and_b32_e32 v1, 0xc0, v4
	s_addc_u32 s26, s1, 0
	v_sub_u32_e32 v1, v2, v1
	v_lshlrev_b32_e32 v2, 1, v3
	v_lshrrev_b32_e32 v4, 2, v3
	v_and_b32_e32 v5, 3, v5
	s_mov_b32 s1, 0x7fffffe0
	v_ashrrev_i16_sdwa v1, v242, sext(v1) dst_sel:DWORD dst_unused:UNUSED_PAD src0_sel:DWORD src1_sel:BYTE_0
	v_and_b32_e32 v2, 24, v2
	v_and_b32_e32 v4, 4, v4
	v_and_or_b32 v5, v3, s1, v5
	v_bfe_i32 v13, v1, 0, 16
	v_or3_b32 v2, v5, v4, v2
	v_add_u32_e32 v1, v12, v13
	v_mul_lo_u32 v14, v3, s0
	v_mul_lo_u32 v2, v2, s0
	v_add_u32_e32 v0, 0x2000, v0
	v_add_lshl_u32 v128, v1, v14, 1
	v_add_lshl_u32 v194, v2, v1, 1
	v_ashrrev_i32_e32 v1, 31, v0
	v_lshrrev_b32_e32 v1, 22, v1
	s_add_i32 s8, s8, s9
	v_add_u32_e32 v1, v0, v1
	s_ashr_i32 s9, s8, 31
	v_ashrrev_i32_e32 v1, 10, v1
	s_lshr_b32 s9, s9, 28
	v_mul_i32_i24_e32 v2, 0x400, v1
	s_add_i32 s9, s8, s9
	v_sub_u32_e32 v0, v0, v2
	s_ashr_i32 s10, s9, 4
	s_and_b32 s9, s9, 0xfff0
	v_lshrrev_b32_e32 v2, 4, v0
	s_sub_i32 s8, s8, s9
	v_bitop3_b32 v0, v2, v0, 32 bitop3:0x6c
	s_bfe_i32 s9, s8, 0x80000
	v_ashrrev_i32_e32 v3, 31, v0
	s_bfe_u32 s9, s9, 0x3000c
	v_lshrrev_b32_e32 v3, 26, v3
	s_add_i32 s9, s8, s9
	v_lshlrev_b32_e32 v2, 3, v1
	v_add_u32_e32 v3, v0, v3
	s_lshl_b32 s11, s10, 3
	s_bfe_i32 s10, s9, 0x80000
	s_and_b32 s9, s9, 0xf8
	v_and_b32_e32 v2, -16, v2
	v_ashrrev_i32_e32 v4, 6, v3
	s_sub_i32 s8, s8, s9
	v_add_u32_e32 v2, v4, v2
	v_and_b32_e32 v4, 3, v4
	s_sext_i32_i8 s8, s8
	v_and_or_b32 v4, v2, s1, v4
	s_ashr_i32 s1, s0, 31
	s_add_i32 s72, s11, s8
	s_lshl_b64 s[6:7], s[0:1], 9
	s_ashr_i32 s8, s72, 31
	s_mul_i32 s8, s6, s8
	s_mul_hi_u32 s9, s6, s72
	s_add_i32 s11, s9, s8
	s_lshr_b64 s[8:9], s[0:1], 23
	s_sext_i32_i16 s15, s10
	s_mul_i32 s9, s8, s72
	s_lshr_b32 s10, s15, 3
	s_add_i32 s11, s11, s9
	s_bfe_i64 s[18:19], s[10:11], 0x100000
	s_ashr_i32 s9, s15, 3
	s_mul_hi_u32 s15, s6, s9
	s_mul_i32 s18, s6, s19
	v_lshlrev_b32_e32 v1, 5, v1
	s_ashr_i32 s13, s14, 6
	s_add_i32 s15, s15, s18
	s_mul_i32 s8, s8, s9
	s_ashr_i32 s12, s14, 8
	v_and_b32_e32 v15, 32, v1
	v_and_b32_e32 v1, 0xc0, v3
	s_lshl_b64 s[4:5], s[0:1], 8
	s_lshl_b32 s30, s13, 10
	s_add_i32 s15, s15, s8
	s_mul_i32 s8, s6, s9
	v_sub_u32_e32 v0, v0, v1
	v_lshlrev_b32_e32 v1, 1, v2
	v_lshrrev_b32_e32 v3, 2, v2
	s_add_u32 s28, s20, s8
	v_ashrrev_i16_sdwa v0, v242, sext(v0) dst_sel:DWORD dst_unused:UNUSED_PAD src0_sel:DWORD src1_sel:BYTE_0
	v_and_b32_e32 v1, 24, v1
	v_and_b32_e32 v3, 4, v3
	s_addc_u32 s29, s26, s15
	s_add_i32 s31, s30, 0
	v_bfe_i32 v16, v0, 0, 16
	v_or3_b32 v1, v4, v3, v1
	s_add_i32 m0, s31, 0x10000
	v_add_u32_e32 v0, v15, v16
	v_mul_lo_u32 v1, v1, s0
	s_add_i32 m0, s31, 0x12000
	v_add_lshl_u32 v132, v1, v0, 1
	s_add_u32 s8, s28, s4
	s_addc_u32 s9, s29, s5
	s_add_i32 m0, s31, 0x14000
	s_mul_i32 s22, s6, s72
	s_add_i32 m0, s31, 0x16000
	s_add_u32 s24, s81, s22
	v_mov_b32_e32 v133, v195
	s_addc_u32 s25, s64, s11
	s_add_i32 s33, s31, 0x2000
	v_mul_lo_u32 v17, v2, s0
	v_lshl_add_u64 v[4:5], s[8:9], 0, v[194:195]
	v_lshl_add_u64 v[6:7], s[8:9], 0, v[132:133]
	s_mov_b32 m0, s31
	s_add_u32 s8, s24, s4
	v_add_lshl_u32 v130, v0, v17, 1
	s_mov_b32 m0, s33
	s_addc_u32 s9, s25, s5
	s_add_i32 s35, s31, 0x4000
	s_mov_b32 m0, s35
	s_add_i32 s42, s31, 0x6000
	s_mov_b32 m0, s42
	v_mov_b32_e32 v129, v195
	v_mov_b32_e32 v131, v195
	s_cmp_eq_u32 s12, 1
	v_lshl_add_u64 v[0:1], s[28:29], 0, v[194:195]
	v_lshl_add_u64 v[2:3], s[28:29], 0, v[132:133]
	v_lshl_add_u64 v[8:9], s[24:25], 0, v[128:129]
	v_lshl_add_u64 v[10:11], s[24:25], 0, v[130:131]
	s_cselect_b64 s[8:9], -1, 0
	s_cmp_lg_u32 s12, 1
	s_cbranch_scc1 .LBB0_337
	s_barrier
.LBB0_337:
	s_sext_i32_i8 s83, s10
	s_lshl_b64 s[18:19], s[92:93], 21
	v_readlane_b32 s10, v253, 60
	s_add_u32 s10, s10, s18
	v_readlane_b32 s11, v253, 61
	s_addc_u32 s11, s11, s19
	s_add_i32 m0, s31, 0x18000
	v_lshl_add_u64 v[0:1], v[0:1], 0, s[38:39]
	s_waitcnt vmcnt(2)
	s_barrier
	v_lshl_add_u64 v[0:1], v[2:3], 0, s[38:39]
	s_add_i32 m0, s31, 0x1a000
	s_add_i32 s50, s31, 0x8000
	v_lshl_add_u64 v[0:1], v[8:9], 0, s[38:39]
	s_mov_b32 m0, s50
	s_add_i32 s51, s31, 0xa000
	v_lshl_add_u64 v[0:1], v[10:11], 0, s[38:39]
	s_mov_b32 m0, s51
	v_bfe_u32 v144, v18, 4, 2
	s_add_i32 m0, s31, 0x1c000
	v_lshl_add_u64 v[0:1], v[4:5], 0, s[38:39]
	v_lshl_add_u64 v[0:1], v[6:7], 0, s[38:39]
	s_add_i32 m0, s31, 0x1e000
	s_lshr_b32 s1, s1, 26
	v_and_b32_e32 v145, 15, v18
	s_add_i32 s1, s0, s1
	v_lshlrev_b32_e32 v19, 4, v144
	v_lshlrev_b32_e32 v18, 2, v18
	s_ashr_i32 s43, s1, 6
	v_lshl_or_b32 v19, v145, 6, v19
	s_lshl_b32 s1, s12, 13
	v_and_b32_e32 v18, 32, v18
	v_bitop3_b32 v20, v19, s1, v18 bitop3:0xde
	s_lshl_b32 s1, s13, 5
	s_and_b32 s49, s1, 0x60
	s_lshl_b32 s48, s12, 6
	s_lshl_b32 s1, s49, 7
	s_cmp_gt_i32 s0, 63
	v_readlane_b32 s88, v253, 36
	v_add_u32_e32 v0, v14, v12
	s_cselect_b64 s[12:13], -1, 0
	s_add_i32 s54, s43, -2
	v_readlane_b32 s89, v253, 37
	v_add_lshl_u32 v0, v0, v13, 1
	v_mov_b32_e32 v1, v195
	v_bitop3_b32 v146, v19, s1, v18 bitop3:0xde
	s_waitcnt vmcnt(6)
	s_cmpk_lt_u32 s14, 0x100
	s_mov_b64 s[0:1], s[88:89]
	v_lshl_add_u64 v[134:135], s[4:5], 0, v[0:1]
	v_add_u32_e32 v0, v17, v15
	s_cselect_b64 s[14:15], -1, 0
	s_add_u32 s55, s0, s18
	v_add_lshl_u32 v0, v0, v16, 1
	s_addc_u32 s68, s1, s19
	v_lshl_add_u64 v[136:137], s[4:5], 0, v[0:1]
	s_mov_b32 s69, 0
	v_add_u32_e32 v147, 0, v20
	s_barrier
	v_readlane_b32 s90, v253, 38
	v_readlane_b32 s91, v253, 39
	s_branch .LBB0_340
